# attention units and SSD items renumbered so each blockIdx%8 class takes one batch element; grid barrier 5 XCD-local like 6/7 (same run-time placement check); w_dn conversion stores write-through, publ
# speedup vs baseline: 1.0196x; 1.0196x over previous
; __device__ __forceinline__ int opaque_tid() { int t = threadIdx.x; asm volatile("" : "+v"(t)); return t; }
; #define LAS __attribute__((address_space(3)))
;     __host__ __device__ bool next(int i, Unit& u) const {
;         const long L = (long)i * G + c; if (L >= nwg) return false;
;         int wgid = (int)L; { const int q = nwg / NXCD, r = nwg % NXCD, xcd = wgid % NXCD, off = wgid / NXCD; wgid = (xcd < r ? xcd * (q + 1) : r * (q + 1) + (xcd - r) * q) + off; }
;         const int nig = WGM * nN, gid = wgid / nig, fm = gid * WGM, gsz = (nM - fm) < WGM ? (nM - fm) : WGM;
;         u.pm = fm + ((wgid % nig) % gsz); u.pn = (wgid % nig) / gsz; return true;
; __device__ __forceinline__ void p0b_mlp_weights(const Args& a, LAS unsigned char* lds) {
;     const int tid = opaque_tid(), lane = tid & 63, wave = tid >> 6;
;     LAS float* scr = (LAS float*)(lds + wave * 16640);
;     const int gw = blockIdx.x * NWAVES + wave, NGW = gridDim.x * NWAVES;
;     constexpr int I_UP = (D_ / 64) * (FF / 64), I_DN = (FF / 64) * (D_ / 64);
;     for (int it = gw; it < I_UP + I_DN; it += NGW) {
;         if (it < I_UP) transpose_item(a.w_up, D_, FF, (bf16*)(a.ws + WS_WUP), a.ln_mlp_g, scr, it, FF / 64, lane);
;         else transpose_item(a.w_dn, FF, D_, (bf16*)(a.ws + WS_WDN), nullptr, scr, it - I_UP, D_ / 64, lane);
.LBB0_257:
	s_or_b64 exec, exec, s[16:17]
	s_add_u32 s16, s92, 0x4000000
	s_addc_u32 s17, s93, 0
	s_ashr_i32 s3, s2, 31
	s_lshr_b32 s18, s3, 29
	s_add_i32 s18, s2, s18
	s_ashr_i32 s0, s18, 3
	s_and_b32 s18, s18, -8
	s_ashr_i32 s95, s94, 31
	s_sub_i32 s7, s2, s18
	s_cmp_lt_i32 s7, 0
	v_writelane_b32 v240, s0, 20
	s_cselect_b64 s[0:1], -1, 0
	v_writelane_b32 v240, s0, 21
	s_cmp_gt_i32 s7, -1
	v_mov_b32_e32 v18, v210
	v_writelane_b32 v240, s1, 22
	s_cselect_b64 s[0:1], -1, 0
	v_writelane_b32 v240, s0, 23
	s_waitcnt lgkmcnt(0)
	s_barrier
	v_writelane_b32 v130, s0, 0
	v_writelane_b32 v130, s10, 1
	v_writelane_b32 v130, s11, 2
	v_writelane_b32 v130, s20, 3
	v_writelane_b32 v130, s21, 4
	v_writelane_b32 v130, s22, 5
	v_writelane_b32 v130, s23, 6
	v_writelane_b32 v130, s24, 7
	v_writelane_b32 v130, s25, 8
	v_writelane_b32 v130, s26, 9
	v_writelane_b32 v130, s42, 10
	v_writelane_b32 v130, s43, 11
	v_writelane_b32 v130, s44, 12
	v_writelane_b32 v130, s45, 13
	v_writelane_b32 v130, s50, 14
	v_writelane_b32 v130, s51, 15
	v_writelane_b32 v130, s64, 16
	v_writelane_b32 v130, s65, 17
	v_writelane_b32 v130, s66, 18
	v_writelane_b32 v130, s67, 19
	v_writelane_b32 v130, s68, 20
	v_writelane_b32 v130, s69, 21
	v_writelane_b32 v130, s70, 22
	v_writelane_b32 v130, s71, 23
	v_writelane_b32 v130, s72, 24
	v_writelane_b32 v130, s73, 25
	v_writelane_b32 v130, s74, 26
	v_writelane_b32 v130, s75, 27
	v_writelane_b32 v130, s76, 28
	v_writelane_b32 v130, s77, 29
	v_writelane_b32 v130, s78, 30
	v_writelane_b32 v130, s79, 31
	v_writelane_b32 v130, s33, 32
	v_writelane_b32 v130, s40, 33
	s_lshl_b32 s40, s94, 1
	s_lshl_b32 s33, s94, 7
	s_add_u32 s10, s92, 0xf6a0000
	v_mov_b32_e32 v0, v210
	s_addc_u32 s11, s93, 0
	v_readlane_b32 s0, v241, 19
	v_ashrrev_i32_e32 v1, 6, v0
	s_add_u32 s50, s92, 0xeea0000
	v_add_u32_e32 v84, s0, v1
	s_mul_i32 s100, s94, 6
	v_subrev_u32_e32 v84, s100, v84
	s_movk_i32 s20, 0x400
	s_addc_u32 s51, s93, 0
	v_cmp_gt_u32_e32 vcc, s20, v84
	s_and_saveexec_b64 s[20:21], vcc
	v_readlane_b32 s64, v241, 2
	v_readlane_b32 s72, v241, 10
	v_readlane_b32 s73, v241, 11
	v_readlane_b32 s74, v241, 12
	v_readlane_b32 s75, v241, 13
	v_readlane_b32 s76, v241, 14
	v_readlane_b32 s77, v241, 15
	v_readlane_b32 s78, v241, 16
	v_readlane_b32 s79, v241, 17
	v_readlane_b32 s65, v241, 3
	v_readlane_b32 s66, v241, 4
	v_readlane_b32 s67, v241, 5
	v_readlane_b32 s68, v241, 6
	v_readlane_b32 s69, v241, 7
	v_readlane_b32 s70, v241, 8
	v_readlane_b32 s71, v241, 9
	s_cbranch_execz .Lw5_554
	s_movk_i32 s24, 0x4100
	v_mul_lo_u32 v2, v1, s24
	v_add_u32_e32 v3, 0, v2
	v_bfe_u32 v85, v0, 4, 2
	v_lshlrev_b32_e32 v2, 2, v0
	v_bfe_u32 v87, v0, 3, 3
	v_lshlrev_b32_e32 v0, 3, v0
	v_and_b32_e32 v6, 56, v0
	v_and_b32_e32 v86, 60, v2
	v_mul_u32_u24_e32 v0, 0x104, v6
	v_lshlrev_b32_e32 v7, 2, v87
	v_lshlrev_b32_e32 v2, 2, v86
	v_add3_u32 v88, v3, v0, v7
	v_mov_b32_e32 v0, 0
	v_readlane_b32 s0, v241, 18
	v_add_u32_e32 v4, v3, v2
	v_mul_u32_u24_e32 v5, 0x104, v85
	v_mov_b32_e32 v3, v0
	v_lshl_add_u32 v96, v1, 6, s0
	s_mul_i32 s101, s94, 0x180
	v_subrev_u32_e32 v96, s101, v96
	v_lshlrev_b32_e32 v1, 2, v1
	s_cmp_lg_u64 s[72:73], 0
	v_lshl_add_u64 v[68:69], s[76:77], 0, v[2:3]
	v_lshl_add_u64 v[70:71], s[74:75], 0, v[2:3]
	v_lshlrev_b32_e32 v2, 1, v6
	v_lshl_add_u32 v1, s2, 5, v1
	v_add_u32_e32 v98, v4, v5
	s_mov_b64 s[22:23], 0
	s_cselect_b64 s[42:43], -1, 0
	v_or_b32_e32 v89, 8, v87
	v_or_b32_e32 v90, 16, v87
	v_or_b32_e32 v91, 24, v87
	v_or_b32_e32 v92, 32, v87
	v_or_b32_e32 v93, 40, v87
	v_or_b32_e32 v94, 48, v87
	v_or_b32_e32 v95, 56, v87
	v_lshl_add_u64 v[72:73], s[10:11], 0, v[2:3]
	v_lshl_add_u64 v[74:75], s[50:51], 0, v[2:3]
	v_add_u32_e32 v97, 0x3d800, v1
	s_lshl_b32 s26, s94, 3
	v_add_u32_e32 v99, 0x410, v98
	v_add_u32_e32 v100, 0x418, v98
	v_add_u32_e32 v101, 0x820, v98
	v_add_u32_e32 v102, 0x828, v98
	v_add_u32_e32 v103, 0xc30, v98
	v_add_u32_e32 v104, 0xc38, v98
	v_add_u32_e32 v105, 0x1040, v98
	v_add_u32_e32 v106, 0x1048, v98
	v_add_u32_e32 v107, 0x1450, v98
	v_add_u32_e32 v108, 0x1458, v98
	v_add_u32_e32 v109, 0x1860, v98
	v_add_u32_e32 v110, 0x1868, v98
	v_add_u32_e32 v111, 0x1c70, v98
	v_add_u32_e32 v112, 0x1c78, v98
	v_add_u32_e32 v113, 0x2080, v98
	v_add_u32_e32 v114, 0x2088, v98
	v_add_u32_e32 v115, 0x2490, v98
	v_add_u32_e32 v116, 0x2498, v98
	v_add_u32_e32 v117, 0x28a0, v98
	v_add_u32_e32 v118, 0x28a8, v98
	v_add_u32_e32 v119, 0x2cb0, v98
	v_add_u32_e32 v120, 0x2cb8, v98
	v_add_u32_e32 v121, 0x30c0, v98
	v_add_u32_e32 v122, 0x30c8, v98
	v_add_u32_e32 v123, 0x34d0, v98
	s_branch .Lw5_517

; #define LAS __attribute__((address_space(3)))
; __device__ __forceinline__ void transpose_item(const float* W, int K, int N, bf16* WT, const float* gain, LAS float* scr, int item, int nblk, int lane) {
;     const int kb = item / nblk, nb = item % nblk, k0 = 64 * kb, n0 = 64 * nb;
;     const int kr = lane >> 4, nc = 4 * (lane & 15);
;     const bool ok = (n0 + nc) < N;
;     f32x4 v[16];
; #pragma unroll
;     for (int i = 0; i < 16; ++i) { v[i] = (f32x4){0.f, 0.f, 0.f, 0.f}; if (ok) v[i] = *(const f32x4*)(W + (size_t)(k0 + 4 * i + kr) * N + n0 + nc); }
;     if (gain) {
; #pragma unroll
;         for (int i = 0; i < 16; ++i) v[i] = v[i] * gain[k0 + 4 * i + kr]; }
; #pragma unroll
;     for (int i = 0; i < 16; ++i) { LAS float* d = scr + (4 * i + kr) * 65 + nc; d[0] = v[i].x; d[1] = v[i].y; d[2] = v[i].z; d[3] = v[i].w; }
;     asm volatile("s_waitcnt lgkmcnt(0)" ::: "memory");
.LBB0_517:
	s_movk_i32 s24, 0x3ff
	v_cmp_lt_i32_e32 vcc, s24, v84
	v_add_u32_e32 v77, 0x34d8, v98
	v_add_u32_e32 v125, 0x38e0, v98
	v_add_u32_e32 v126, 0x38e8, v98
	v_add_u32_e32 v127, 0x3cf0, v98
	v_add_u32_e32 v128, 0x3cf8, v98
	v_add_u32_e32 v124, 0x400, v88
	s_and_saveexec_b64 s[24:25], vcc
	s_xor_b64 s[44:45], exec, s[24:25]
	s_cbranch_execz .LBB0_519
	v_and_b32_e32 v1, 0x3ffc0, v97
	v_and_b32_e32 v66, 0x3c0, v96
	v_or_b32_e32 v4, v1, v85
	v_lshlrev_b32_e32 v2, 2, v66
	v_mov_b32_e32 v3, v0
	v_lshl_add_u64 v[2:3], v[68:69], 0, v[2:3]
	v_lshlrev_b32_e32 v4, 12, v4
	v_mov_b32_e32 v5, v0
	v_lshl_add_u64 v[62:63], v[2:3], 0, v[4:5]
	v_add_co_u32_e32 v6, vcc, 0x4000, v62
	s_nop 1
	v_addc_co_u32_e32 v7, vcc, 0, v63, vcc
	v_add_co_u32_e32 v10, vcc, 0x8000, v62
	global_load_dwordx4 v[2:5], v[62:63], off
	s_nop 0
	global_load_dwordx4 v[6:9], v[6:7], off
	v_addc_co_u32_e32 v11, vcc, 0, v63, vcc
	v_add_co_u32_e32 v14, vcc, 0xc000, v62
	s_nop 1
	v_addc_co_u32_e32 v15, vcc, 0, v63, vcc
	v_add_co_u32_e32 v18, vcc, 0x10000, v62
	global_load_dwordx4 v[10:13], v[10:11], off
	s_nop 0
	global_load_dwordx4 v[14:17], v[14:15], off
	v_addc_co_u32_e32 v19, vcc, 0, v63, vcc
	v_add_co_u32_e32 v22, vcc, 0x14000, v62
	s_nop 1
	v_addc_co_u32_e32 v23, vcc, 0, v63, vcc
	v_add_co_u32_e32 v26, vcc, 0x18000, v62
	global_load_dwordx4 v[18:21], v[18:19], off
	s_nop 0
	global_load_dwordx4 v[22:25], v[22:23], off
	v_addc_co_u32_e32 v27, vcc, 0, v63, vcc
	v_add_co_u32_e32 v30, vcc, 0x1c000, v62
	s_nop 1
	v_addc_co_u32_e32 v31, vcc, 0, v63, vcc
	v_add_co_u32_e32 v34, vcc, 0x20000, v62
	global_load_dwordx4 v[26:29], v[26:27], off
	s_nop 0
	global_load_dwordx4 v[30:33], v[30:31], off
	v_addc_co_u32_e32 v35, vcc, 0, v63, vcc
	v_add_co_u32_e32 v38, vcc, 0x24000, v62
	s_nop 1
	v_addc_co_u32_e32 v39, vcc, 0, v63, vcc
	v_add_co_u32_e32 v42, vcc, 0x28000, v62
	global_load_dwordx4 v[34:37], v[34:35], off
	s_nop 0
	global_load_dwordx4 v[38:41], v[38:39], off
	v_addc_co_u32_e32 v43, vcc, 0, v63, vcc
	v_add_co_u32_e32 v46, vcc, 0x2c000, v62
	s_nop 1
	v_addc_co_u32_e32 v47, vcc, 0, v63, vcc
	v_add_co_u32_e32 v50, vcc, 0x30000, v62
	global_load_dwordx4 v[42:45], v[42:43], off
	s_nop 0
	global_load_dwordx4 v[46:49], v[46:47], off
	v_addc_co_u32_e32 v51, vcc, 0, v63, vcc
	v_add_co_u32_e32 v54, vcc, 0x34000, v62
	s_nop 1
	v_addc_co_u32_e32 v55, vcc, 0, v63, vcc
	global_load_dwordx4 v[50:53], v[50:51], off
	s_nop 0
	global_load_dwordx4 v[54:57], v[54:55], off
	v_add_co_u32_e32 v58, vcc, 0x38000, v62
	s_nop 1
	v_addc_co_u32_e32 v59, vcc, 0, v63, vcc
	global_load_dwordx4 v[58:61], v[58:59], off
	v_add_co_u32_e32 v62, vcc, 0x3c000, v62
	s_nop 1
	v_addc_co_u32_e32 v63, vcc, 0, v63, vcc
	global_load_dwordx4 v[62:65], v[62:63], off
	s_waitcnt vmcnt(15)
	ds_write2_b32 v98, v2, v3 offset1:1
	ds_write2_b32 v98, v4, v5 offset0:2 offset1:3
	s_waitcnt vmcnt(14)
	ds_write2_b32 v99, v6, v7 offset1:1
	ds_write2_b32 v100, v8, v9 offset1:1
	s_waitcnt vmcnt(13)
	ds_write2_b32 v101, v10, v11 offset1:1
	ds_write2_b32 v102, v12, v13 offset1:1
	s_waitcnt vmcnt(12)
	ds_write2_b32 v103, v14, v15 offset1:1
	ds_write2_b32 v104, v16, v17 offset1:1
	s_waitcnt vmcnt(11)
	ds_write2_b32 v105, v18, v19 offset1:1
	ds_write2_b32 v106, v20, v21 offset1:1
	s_waitcnt vmcnt(10)
	ds_write2_b32 v107, v22, v23 offset1:1
	ds_write2_b32 v108, v24, v25 offset1:1
	s_waitcnt vmcnt(9)
	ds_write2_b32 v109, v26, v27 offset1:1
	ds_write2_b32 v110, v28, v29 offset1:1
	s_waitcnt vmcnt(8)
	ds_write2_b32 v111, v30, v31 offset1:1
	ds_write2_b32 v112, v32, v33 offset1:1
	s_waitcnt vmcnt(7)
	ds_write2_b32 v113, v34, v35 offset1:1
	ds_write2_b32 v114, v36, v37 offset1:1
	s_waitcnt vmcnt(6)
	ds_write2_b32 v115, v38, v39 offset1:1
	ds_write2_b32 v116, v40, v41 offset1:1
	s_waitcnt vmcnt(5)
	ds_write2_b32 v117, v42, v43 offset1:1
	ds_write2_b32 v118, v44, v45 offset1:1
	s_waitcnt vmcnt(4)
	ds_write2_b32 v119, v46, v47 offset1:1
	ds_write2_b32 v120, v48, v49 offset1:1
	s_waitcnt vmcnt(3)
	ds_write2_b32 v121, v50, v51 offset1:1
	ds_write2_b32 v122, v52, v53 offset1:1
	s_waitcnt vmcnt(2)
	ds_write2_b32 v123, v54, v55 offset1:1
	ds_write2_b32 v77, v56, v57 offset1:1
	s_waitcnt vmcnt(1)
	ds_write2_b32 v125, v58, v59 offset1:1
	ds_write2_b32 v126, v60, v61 offset1:1
	s_waitcnt vmcnt(0)
	ds_write2_b32 v127, v62, v63 offset1:1
	ds_write2_b32 v128, v64, v65 offset1:1
	s_waitcnt lgkmcnt(0)
; #define LAS __attribute__((address_space(3)))
; __device__ __forceinline__ unsigned pk2(float lo, float hi) { f32x2 v = {lo, hi}; bf16x2_t b = __builtin_convertvector(v, bf16x2_t); return __builtin_bit_cast(unsigned, b); }
; __device__ __forceinline__ void transpose_item(const float* W, int K, int N, bf16* WT, const float* gain, LAS float* scr, int item, int nblk, int lane) {
;     ...
;     const int c = lane & 7;
; #pragma unroll
;     for (int j = 0; j < 8; ++j) { const int n = (lane >> 3) + 8 * j; const LAS float* sp = scr + (8 * c) * 65 + n;
;         u32x4 o; o.x = pk2(sp[0 * 65], sp[1 * 65]); o.y = pk2(sp[2 * 65], sp[3 * 65]); o.z = pk2(sp[4 * 65], sp[5 * 65]); o.w = pk2(sp[6 * 65], sp[7 * 65]);
;         *(u32x4*)(WT + (size_t)(n0 + n) * K + k0 + 8 * c) = o; }
;     asm volatile("s_waitcnt lgkmcnt(0)" ::: "memory");
	ds_read2_b32 v[6:7], v88 offset0:65 offset1:73
	ds_read2_b32 v[8:9], v88 offset1:8
	ds_read2_b32 v[10:11], v88 offset0:130 offset1:138
	ds_read2_b32 v[12:13], v88 offset0:195 offset1:203
	ds_read2_b32 v[14:15], v124 offset0:4 offset1:12
	ds_read2_b32 v[16:17], v124 offset0:69 offset1:77
	ds_read2_b32 v[18:19], v124 offset0:134 offset1:142
	ds_read2_b32 v[20:21], v124 offset0:199 offset1:207
	v_lshlrev_b32_e32 v2, 1, v1
	v_mov_b32_e32 v3, v0
	v_or_b32_e32 v1, v66, v87
	v_lshl_add_u64 v[22:23], v[72:73], 0, v[2:3]
	v_lshlrev_b32_e32 v24, 13, v1
	v_mov_b32_e32 v25, v0
	s_waitcnt lgkmcnt(6)
	v_cvt_pk_bf16_f32 v2, v8, v6
	s_waitcnt lgkmcnt(4)
	v_cvt_pk_bf16_f32 v3, v10, v12
	s_waitcnt lgkmcnt(2)
	v_cvt_pk_bf16_f32 v4, v14, v16
	s_waitcnt lgkmcnt(0)
	v_cvt_pk_bf16_f32 v5, v18, v20
	v_lshl_add_u64 v[24:25], v[22:23], 0, v[24:25]
	global_store_dwordx4 v[24:25], v[2:5], off sc0 sc1
	v_or_b32_e32 v1, v66, v89
	v_lshlrev_b32_e32 v6, 13, v1
	v_cvt_pk_bf16_f32 v2, v9, v7
	v_cvt_pk_bf16_f32 v3, v11, v13
	v_cvt_pk_bf16_f32 v4, v15, v17
	v_cvt_pk_bf16_f32 v5, v19, v21
	ds_read2_b32 v[8:9], v88 offset0:81 offset1:89
	ds_read2_b32 v[10:11], v88 offset0:16 offset1:24
	ds_read2_b32 v[12:13], v88 offset0:146 offset1:154
	ds_read2_b32 v[14:15], v88 offset0:211 offset1:219
	ds_read2_b32 v[16:17], v124 offset0:20 offset1:28
	ds_read2_b32 v[18:19], v124 offset0:85 offset1:93
	ds_read2_b32 v[20:21], v124 offset0:150 offset1:158
	ds_read2_b32 v[24:25], v124 offset0:215 offset1:223
	v_mov_b32_e32 v7, v0
	v_lshl_add_u64 v[6:7], v[22:23], 0, v[6:7]
	v_or_b32_e32 v1, v66, v90
	global_store_dwordx4 v[6:7], v[2:5], off sc0 sc1
	v_lshlrev_b32_e32 v6, 13, v1
	v_mov_b32_e32 v7, v0
	s_waitcnt lgkmcnt(6)
	v_cvt_pk_bf16_f32 v2, v10, v8
	s_waitcnt lgkmcnt(4)
	v_cvt_pk_bf16_f32 v3, v12, v14
	s_waitcnt lgkmcnt(2)
	v_cvt_pk_bf16_f32 v4, v16, v18
	s_waitcnt lgkmcnt(0)
	v_cvt_pk_bf16_f32 v5, v20, v24
	v_lshl_add_u64 v[6:7], v[22:23], 0, v[6:7]
	global_store_dwordx4 v[6:7], v[2:5], off sc0 sc1
	v_or_b32_e32 v1, v66, v91
	v_lshlrev_b32_e32 v6, 13, v1
	v_cvt_pk_bf16_f32 v2, v11, v9
	v_cvt_pk_bf16_f32 v3, v13, v15
	v_cvt_pk_bf16_f32 v4, v17, v19
	v_cvt_pk_bf16_f32 v5, v21, v25
	ds_read2_b32 v[8:9], v88 offset0:32 offset1:40
	ds_read2_b32 v[10:11], v88 offset0:97 offset1:105
	ds_read2_b32 v[12:13], v88 offset0:162 offset1:170
	ds_read2_b32 v[14:15], v88 offset0:227 offset1:235
	ds_read2_b32 v[16:17], v124 offset0:36 offset1:44
	ds_read2_b32 v[18:19], v124 offset0:101 offset1:109
	ds_read2_b32 v[20:21], v124 offset0:166 offset1:174
	ds_read2_b32 v[24:25], v124 offset0:231 offset1:239
	v_mov_b32_e32 v7, v0
	v_lshl_add_u64 v[6:7], v[22:23], 0, v[6:7]
	v_or_b32_e32 v1, v66, v92
	global_store_dwordx4 v[6:7], v[2:5], off sc0 sc1
	v_lshlrev_b32_e32 v6, 13, v1
	v_mov_b32_e32 v7, v0
	s_waitcnt lgkmcnt(6)
	v_cvt_pk_bf16_f32 v2, v8, v10
	s_waitcnt lgkmcnt(4)
	v_cvt_pk_bf16_f32 v3, v12, v14
	s_waitcnt lgkmcnt(2)
	v_cvt_pk_bf16_f32 v4, v16, v18
	s_waitcnt lgkmcnt(0)
	v_cvt_pk_bf16_f32 v5, v20, v24
	v_lshl_add_u64 v[6:7], v[22:23], 0, v[6:7]
	global_store_dwordx4 v[6:7], v[2:5], off sc0 sc1
	v_or_b32_e32 v1, v66, v93
	v_lshlrev_b32_e32 v6, 13, v1
	v_cvt_pk_bf16_f32 v2, v9, v11
	v_cvt_pk_bf16_f32 v3, v13, v15
	v_cvt_pk_bf16_f32 v4, v17, v19
	v_cvt_pk_bf16_f32 v5, v21, v25
	ds_read2_b32 v[8:9], v88 offset0:48 offset1:56
	ds_read2_b32 v[10:11], v88 offset0:113 offset1:121
	ds_read2_b32 v[12:13], v88 offset0:178 offset1:186
	ds_read2_b32 v[14:15], v88 offset0:243 offset1:251
	ds_read2_b32 v[16:17], v124 offset0:52 offset1:60
	ds_read2_b32 v[18:19], v124 offset0:117 offset1:125
	ds_read2_b32 v[20:21], v124 offset0:182 offset1:190
	ds_read2_b32 v[24:25], v124 offset0:247 offset1:255
	v_mov_b32_e32 v7, v0
	v_lshl_add_u64 v[6:7], v[22:23], 0, v[6:7]
	v_or_b32_e32 v1, v66, v94
	global_store_dwordx4 v[6:7], v[2:5], off sc0 sc1
	v_lshlrev_b32_e32 v6, 13, v1
	v_mov_b32_e32 v7, v0
	s_waitcnt lgkmcnt(6)
	v_cvt_pk_bf16_f32 v2, v8, v10
	s_waitcnt lgkmcnt(4)
	v_cvt_pk_bf16_f32 v3, v12, v14
	s_waitcnt lgkmcnt(2)
	v_cvt_pk_bf16_f32 v4, v16, v18
	s_waitcnt lgkmcnt(0)
	v_cvt_pk_bf16_f32 v5, v20, v24
	v_lshl_add_u64 v[6:7], v[22:23], 0, v[6:7]
	v_or_b32_e32 v1, v66, v95
	global_store_dwordx4 v[6:7], v[2:5], off sc0 sc1
	v_lshlrev_b32_e32 v6, 13, v1
	v_mov_b32_e32 v7, v0
	v_cvt_pk_bf16_f32 v2, v9, v11
	v_cvt_pk_bf16_f32 v3, v13, v15
	v_cvt_pk_bf16_f32 v4, v17, v19
	v_cvt_pk_bf16_f32 v5, v21, v25
	v_lshl_add_u64 v[6:7], v[22:23], 0, v[6:7]
	global_store_dwordx4 v[6:7], v[2:5], off sc0 sc1
	s_waitcnt lgkmcnt(0)

; __device__ __forceinline__ int opaque_tid() { int t = threadIdx.x; asm volatile("" : "+v"(t)); return t; }
; #define AT_LOAD(j) do { kr0 = *(const u32x4*)(Kp + (size_t)(j) * 12288 + kc0 * 16); if (tid < 256) kr1 = *(const u32x4*)(Kp + (size_t)(j) * 12288 + kc1 * 16); \
;         vr = *(const u32x4*)(Vp + (size_t)vrow * S_ + (j) * 64 + vc8 * 8); } while (0)
; #define AT_STORE(buf) do { LAS unsigned char* bb = lds + (buf) * AT_BUF; *(LAS u32x4*)(bb + koff0) = kr0; if (tid < 256) *(LAS u32x4*)(bb + koff1) = kr1; \
;         *(LAS u32x2*)(bb + voff) = (u32x2){vr.x, vr.y}; *(LAS u32x2*)(bb + voff + 16) = (u32x2){vr.z, vr.w}; } while (0)
; __device__ __forceinline__ void attn_item(LAS unsigned char* lds, const bf16* Q, const bf16* Kg, const bf16* Vt, bf16* O, float* ssqa, int b, int h, int qb, float mb) {
;     const int tid = opaque_tid(), lane = tid & 63, w = tid >> 6, r = lane & 31, hh = lane >> 5;
;     const size_t bh = (size_t)(b * 8 + h);
;     const int qrow = qb * 256 + w * 32 + r;
;     bf16x8 qf[6];
;     { const bf16* Qp = Q + (bh * S_ + qrow) * 96 + 8 * hh;
; #pragma unroll
;       for (int s = 0; s < 6; ++s) qf[s] = *(const bf16x8*)(Qp + 16 * s); }
;     const unsigned char* Kp = (const unsigned char*)(Kg + bh * S_ * 96);
;     const bf16* Vp = Vt + bh * 64 * S_;
;     const int vrow = tid >> 3, vc8 = tid & 7;
;     const int kc0 = tid, kc1 = tid + 512;
;     const unsigned koff0 = (kc0 / 12) * AT_KROW + (kc0 % 12) * 16, koff1 = (kc1 / 12) * AT_KROW + (kc1 % 12) * 16;
;     const unsigned voff = AT_KBYTES + vrow * AT_VROW + (vc8 >> 1) * 32 + (vc8 & 1) * 8;
;     u32x4 kr0, kr1 = {0, 0, 0, 0}, vr;
;     ...
;     __syncthreads();
;     AT_LOAD(0); AT_STORE(0);
;     __syncthreads();
; __global__ void __launch_bounds__(NTHREADS, 2) fwd_megakernel(Args a) {
;     ...
;         for (int u = bx; u < 512; u += G) { const int qb = u & 7, h = (u >> 3) & 7, b = u >> 6; attn_item(lds, (const bf16*)(ws + WS_HB), (const bf16*)(ws + WS_K), (const bf16*)(ws + WS_VT), (bf16*)(ws + WS_MIXRAW), (float*)(ws + WS_SSQA), b, h, qb, mb); }
.LBB0_563:
	s_and_b32 s98, s30, 7
	s_lshl_b32 s98, s98, 6
	s_bfe_u32 s99, s30, 0x50003
	s_or_b32 s98, s98, s99
	s_bfe_u32 s99, s30, 0x10008
	s_lshl_b32 s99, s99, 5
	s_or_b32 s99, s99, s98
	v_mov_b32_e32 v32, v210
	s_ashr_i32 s40, s99, 6
	s_lshl_b32 s33, s99, 8
	v_ashrrev_i32_e32 v135, 6, v32
	s_bfe_u32 s31, s99, 0x30003
	s_lshl_b32 s41, s40, 3
	s_and_b32 s33, s33, 0x700
	v_lshlrev_b32_e32 v106, 5, v135
	v_and_b32_e32 v107, 31, v32
	s_or_b32 s24, s41, s31
	v_add_u32_e32 v16, s33, v106
	s_ashr_i32 s25, s24, 31
	v_or_b32_e32 v108, v16, v107
	s_lshl_b64 s[34:35], s[24:25], 11
	v_ashrrev_i32_e32 v109, 31, v108
	v_lshl_add_u64 v[16:17], s[34:35], 0, v[108:109]
	v_bfe_u32 v20, v32, 5, 1
	v_mad_u64_u32 v[18:19], s[34:35], v16, s28, v[104:105]
	v_mad_i32_i24 v19, v17, s28, v19
	v_lshlrev_b32_e32 v110, 4, v20
	v_mov_b32_e32 v111, v65
	v_lshl_add_u64 v[16:17], v[18:19], 0, v[110:111]
	global_load_dwordx4 v[88:91], v[16:17], off
	global_load_dwordx4 v[84:87], v[16:17], off offset:32
	global_load_dwordx4 v[80:83], v[16:17], off offset:64
	global_load_dwordx4 v[76:79], v[16:17], off offset:96
	global_load_dwordx4 v[72:75], v[16:17], off offset:128
	global_load_dwordx4 v[68:71], v[16:17], off offset:160
	s_mul_i32 s35, s24, 0x60000
	s_mul_hi_i32 s34, s24, 0x60000
	s_add_u32 s44, s48, s35
	v_lshlrev_b32_e32 v24, 4, v32
	s_addc_u32 s45, s49, s34
	v_ashrrev_i32_e32 v25, 31, v24
	v_lshl_add_u64 v[16:17], s[44:45], 0, v[24:25]
	s_barrier
	global_load_dwordx4 v[16:19], v[16:17], off
	v_add_u32_e32 v20, 0x200, v32
	v_mov_b32_e32 v66, v65
	v_mov_b32_e32 v67, v65
	s_movk_i32 s34, 0x100
	v_mov_b32_e32 v64, v65
	v_lshlrev_b32_e32 v26, 4, v20
	v_mov_b64_e32 v[94:95], v[66:67]
	v_cmp_gt_i32_e32 vcc, s34, v32
	v_ashrrev_i32_e32 v27, 31, v26
	v_mov_b64_e32 v[92:93], v[64:65]
	s_and_saveexec_b64 s[46:47], vcc
	s_cbranch_execz .LBB0_565
	v_lshl_add_u64 v[22:23], s[44:45], 0, v[26:27]
	global_load_dwordx4 v[92:95], v[22:23], off
.LBB0_565:
	s_or_b64 exec, exec, s[46:47]
	v_mul_hi_i32 v21, v32, s29
	v_lshrrev_b32_e32 v22, 31, v21
	v_lshrrev_b32_e32 v21, 1, v21
	v_add_u32_e32 v21, v21, v22
	s_lshl_b64 s[24:25], s[24:25], 18
	v_ashrrev_i32_e32 v28, 3, v32
	v_add_lshl_u32 v138, v21, v32, 4
	v_mul_hi_i32 v21, v20, s29
	s_add_u32 s24, s52, s24
	v_lshrrev_b32_e32 v22, 31, v21
	v_lshrrev_b32_e32 v21, 1, v21
	v_ashrrev_i32_e32 v29, 31, v28
	s_addc_u32 s25, s53, s25
	v_and_b32_e32 v111, 7, v32
	v_add_u32_e32 v21, v21, v22
	v_lshlrev_b64 v[30:31], 12, v[28:29]
	v_add_lshl_u32 v139, v21, v20, 4
	v_lshl_add_u64 v[20:21], s[24:25], 0, v[30:31]
	v_lshlrev_b32_e32 v64, 4, v111
	v_lshl_add_u64 v[20:21], v[20:21], 0, v[64:65]
	global_load_dwordx4 v[20:23], v[20:21], off
	v_add_u32_e32 v29, 0, v138
	s_waitcnt vmcnt(1)
	ds_write_b128 v29, v[16:19]
	s_and_saveexec_b64 s[24:25], vcc
	v_add_u32_e32 v16, 0, v139
	ds_write_b128 v16, v[92:95]
	s_or_b64 exec, exec, s[24:25]
	s_movk_i32 s25, 0x90
	s_lshr_b32 s24, s99, 3
	v_mul_lo_u32 v16, v28, s25
	v_lshlrev_b32_e32 v18, 3, v32
	s_and_b32 s24, s24, 7
	v_and_b32_e32 v17, 0x60, v64
	v_and_or_b32 v16, v18, 8, v16
	v_add_u32_e32 v140, v16, v17
	s_add_i32 s24, s41, s24
	v_add_u32_e32 v16, 0, v140
	s_ashr_i32 s25, s24, 31
	v_add_u32_e32 v16, 0x3000, v16
	s_lshl_b64 s[34:35], s[24:25], 18
	s_mul_hi_i32 s25, s24, 0x60000
	s_mul_i32 s24, s24, 0x60000
	s_waitcnt vmcnt(0)
	ds_write2_b64 v16, v[20:21], v[22:23] offset0:128 offset1:130
	v_lshl_add_u64 v[16:17], s[34:35], 0, v[30:31]
	s_add_u32 s24, s26, s24
	v_lshl_add_u64 v[16:17], v[16:17], 0, v[64:65]
	s_addc_u32 s25, s27, s25
	v_mov_b32_e32 v66, 0
	v_and_b32_e32 v137, 63, v32
	v_lshlrev_b32_e32 v136, 3, v111
	v_mul_u32_u24_e32 v141, 0xd0, v107
	v_mul_u32_u24_e32 v142, 0x90, v107
	v_lshl_add_u64 v[112:113], s[22:23], 0, v[16:17]
	v_lshl_add_u64 v[114:115], s[24:25], 0, v[24:25]
	v_lshl_add_u64 v[116:117], s[24:25], 0, v[26:27]
	s_mov_b32 s44, 0
	v_mov_b32_e32 v67, v66
	v_mov_b32_e32 v16, v66
	v_mov_b32_e32 v17, v66
	v_mov_b32_e32 v18, v66
	v_mov_b32_e32 v19, v66
	v_mov_b32_e32 v20, v66
	v_mov_b32_e32 v21, v66
	v_mov_b32_e32 v22, v66
	v_mov_b32_e32 v23, v66
	v_mov_b32_e32 v24, v66
	v_mov_b32_e32 v25, v66
	v_mov_b32_e32 v26, v66
	v_mov_b32_e32 v27, v66
	v_mov_b32_e32 v28, v66
	v_mov_b32_e32 v29, v66
	v_mov_b32_e32 v30, v66
	v_mov_b32_e32 v31, v66
	v_mov_b32_e32 v32, v66
	v_mov_b32_e32 v33, v66
	v_mov_b32_e32 v34, v66
	v_mov_b32_e32 v35, v66
	v_mov_b32_e32 v36, v66
	v_mov_b32_e32 v37, v66
	v_mov_b32_e32 v38, v66
	v_mov_b32_e32 v39, v66
	v_mov_b32_e32 v40, v66
	v_mov_b32_e32 v41, v66
	v_mov_b32_e32 v42, v66
	v_mov_b32_e32 v43, v66
	v_mov_b32_e32 v44, v66
	v_mov_b32_e32 v45, v66
	v_mov_b32_e32 v46, v66
	v_mov_b32_e32 v47, v66
	s_waitcnt lgkmcnt(0)
	s_barrier
	s_branch .LBB0_569

; __device__ __forceinline__ int opaque_tid() { int t = threadIdx.x; asm volatile("" : "+v"(t)); return t; }
; __device__ __forceinline__ void ssd_item(LAS unsigned char* lds, const Args& a, int b, int hp, int qb) {
;     const int tid = opaque_tid(), lane = tid & 63, w = tid >> 6, r = lane & 31, hh = lane >> 5;
;     const int g = hp >> 1, h0 = hp * 2;
;     const bf16* Bm = (const bf16*)(a.ws + WS_BM); const bf16* Cm = (const bf16*)(a.ws + WS_CM); const bf16* Xt = (const bf16*)(a.ws + WS_XT);
;     const float* vec = (const float*)(a.ws + WS_VEC);
;     const size_t VS = (size_t)NB * 8 * S_;
;     const int l0 = qb * 256 + w * 32, l = l0 + r;
;     bf16x8 cf[8];
;     { const bf16* Cp = Cm + ((size_t)(b * 2 + g) * S_ + l) * 128 + 8 * hh;
; #pragma unroll
;       for (int s = 0; s < 8; ++s) cf[s] = *(const bf16x8*)(Cp + 16 * s); }
;     float afl[2], rbl[2], dsk[2];
; #pragma unroll
;     for (int hd = 0; hd < 2; ++hd) { const float* vb = vec + ((size_t)b * 8 + h0 + hd) * S_; afl[hd] = vb[l]; rbl[hd] = vb[VS + l]; dsk[hd] = a.d_skip[h0 + hd]; }
;     const unsigned char* Bp = (const unsigned char*)(Bm + (size_t)(b * 2 + g) * S_ * 128);
;     const int xrow = tid >> 3, xc8 = tid & 7;
;     const bf16* Xp0 = Xt + ((size_t)(b * 8 + h0) * 64 + xrow) * S_ + xc8 * 8;
;     const bf16* Xp1 = Xp0 + (size_t)64 * S_;
;     const int bc0 = tid, bc1 = tid + 512;
;     const unsigned boff0 = (bc0 >> 4) * SD_BROW + (bc0 & 15) * 16, boff1 = (bc1 >> 4) * SD_BROW + (bc1 & 15) * 16;
;     const unsigned xoff = SD_BBYTES + xrow * SD_XROW + (xc8 >> 1) * 32 + (xc8 & 1) * 8;
;     const int vhd = tid / 96, vrem = tid % 96, varr = vrem >> 4, vc = vrem & 15;
;     const float* vsrc = vec + (size_t)varr * VS + ((size_t)b * 8 + h0 + vhd) * S_ + 4 * vc;
;     const unsigned voff = SD_VEC + ((vhd * 6 + varr) * 64 + 4 * vc) * 4;
;     u32x4 br0, br1, xr0, xr1; f32x4 vr = {0.f, 0.f, 0.f, 0.f};
;     ...
;     const int j0 = qb * 4, j1 = j0 + 4;
;     __syncthreads();
;     SD_LOAD(j0); SD_STORE(j0 & 1);
; __global__ void __launch_bounds__(NTHREADS, 2) fwd_megakernel(Args a) {
;     ...
;         for (int it = bx; it < 256; it += G) { const int qb = it & 7, hp = (it >> 3) & 3, b = it >> 5; ssd_item(lds, a, b, hp, qb); }
.LBB0_588:
	s_and_b32 s98, s74, 7
	s_lshl_b32 s98, s98, 5
	s_bfe_u32 s99, s74, 0x50003
	s_or_b32 s99, s99, s98
	s_lshr_b32 s27, s99, 3
	s_ashr_i32 s20, s99, 5
	s_and_b32 s78, s99, 7
	v_mov_b32_e32 v162, v210
	s_bfe_u32 s75, s27, 0x10001
	s_lshl_b32 s26, s20, 1
	s_lshl_b32 s77, s78, 8
	v_ashrrev_i32_e32 v174, 6, v162
	s_or_b32 s0, s75, s26
	v_and_b32_e32 v165, 31, v162
	v_lshl_add_u32 v164, v174, 5, s77
	s_ashr_i32 s1, s0, 31
	s_bfe_u32 s76, s99, 0x20003
	v_or_b32_e32 v100, v164, v165
	s_lshl_b64 s[28:29], s[0:1], 19
	v_ashrrev_i32_e32 v101, 31, v100
	s_add_u32 s0, s33, s28
	v_bfe_u32 v18, v162, 5, 1
	s_waitcnt lgkmcnt(0)
	v_lshlrev_b64 v[0:1], 8, v[100:101]
	s_addc_u32 s1, s6, s29
	s_ashr_i32 s21, s20, 31
	v_lshl_add_u64 v[0:1], s[0:1], 0, v[0:1]
	v_lshlrev_b32_e32 v160, 4, v18
	s_lshl_b32 s30, s76, 1
	s_lshl_b64 s[0:1], s[20:21], 3
	v_lshl_add_u64 v[0:1], v[0:1], 0, v[160:161]
	s_or_b32 s24, s0, s30
	s_mov_b32 s25, s1
	global_load_dwordx4 v[156:159], v[0:1], off
	global_load_dwordx4 v[152:155], v[0:1], off offset:32
	global_load_dwordx4 v[148:151], v[0:1], off offset:64
	global_load_dwordx4 v[144:147], v[0:1], off offset:96
	global_load_dwordx4 v[140:143], v[0:1], off offset:128
	global_load_dwordx4 v[136:139], v[0:1], off offset:160
	global_load_dwordx4 v[132:135], v[0:1], off offset:192
	global_load_dwordx4 v[128:131], v[0:1], off offset:224
	v_lshl_add_u64 v[0:1], v[100:101], 2, s[18:19]
	s_lshl_b64 s[52:53], s[24:25], 13
	v_lshl_add_u64 v[2:3], v[0:1], 0, s[52:53]
	v_add_co_u32_e32 v4, vcc, s36, v2
	s_lshl_b32 s22, s76, 3
	s_nop 0
	v_addc_co_u32_e32 v5, vcc, 0, v3, vcc
	global_load_dword v177, v[2:3], off
	global_load_dword v178, v[4:5], off
	v_mov_b32_e32 v2, s22
	s_or_b32 s22, s52, 0x2000
	s_add_u32 s34, s7, s28
	s_addc_u32 s29, s14, s29
	s_lshl_b32 s28, s20, 3
	s_mov_b64 s[80:81], s[62:63]
	v_readlane_b32 s56, v241, 2
	s_mov_b32 s23, s53
	s_or_b32 s54, s30, s28
	v_readlane_b32 s57, v241, 3
	v_readlane_b32 s58, v241, 4
	v_readlane_b32 s59, v241, 5
	v_lshl_add_u64 v[0:1], v[0:1], 0, s[22:23]
	s_ashr_i32 s55, s54, 31
	v_ashrrev_i32_e32 v12, 3, v162
	s_lshl_b64 s[56:57], s[54:55], 18
	v_ashrrev_i32_e32 v13, 31, v12
	global_load_dwordx2 v[102:103], v2, s[58:59]
	v_add_co_u32_e32 v2, vcc, s36, v0
	s_add_u32 s30, s4, s56
	s_nop 0
	v_addc_co_u32_e32 v3, vcc, 0, v1, vcc
	global_load_dword v179, v[0:1], off
	global_load_dword v176, v[2:3], off
	v_and_b32_e32 v0, 7, v162
	s_addc_u32 s31, s5, s57
	v_lshlrev_b64 v[2:3], 12, v[12:13]
	v_lshl_add_u64 v[4:5], s[30:31], 0, v[2:3]
	v_lshlrev_b32_e32 v0, 4, v0
	v_mov_b32_e32 v1, v161
	s_lshl_b32 s30, s78, 16
	v_lshl_add_u64 v[8:9], v[4:5], 0, v[0:1]
	v_add_u32_e32 v104, 0x200, v162
	v_lshlrev_b32_e32 v4, 4, v162
	s_add_u32 s30, s34, s30
	s_addc_u32 s31, s29, 0
	v_ashrrev_i32_e32 v5, 31, v4
	v_lshlrev_b32_e32 v6, 4, v104
	s_lshl_b32 s44, s78, 9
	v_lshl_add_u64 v[10:11], s[30:31], 0, v[4:5]
	v_ashrrev_i32_e32 v7, 31, v6
	v_lshl_add_u64 v[8:9], v[8:9], 0, s[44:45]
	s_barrier
	v_lshl_add_u64 v[14:15], s[30:31], 0, v[6:7]
	global_load_dwordx4 v[80:83], v[10:11], off
	global_load_dwordx4 v[84:87], v[14:15], off
	v_add_co_u32_e32 v10, vcc, 0x40000, v8
	s_mov_b32 s29, 0x2aaaaaab
	s_nop 0
	v_addc_co_u32_e32 v11, vcc, 0, v9, vcc
	global_load_dwordx4 v[88:91], v[8:9], off
	global_load_dwordx4 v[92:95], v[10:11], off
	v_mul_hi_i32 v1, v162, s29
	v_lshrrev_b32_e32 v8, 31, v1
	v_ashrrev_i32_e32 v1, 4, v1
	v_add_u32_e32 v8, v1, v8
	s_movk_i32 s29, 0x60
	v_mul_lo_u32 v1, v8, s29
	v_sub_u32_e32 v1, v162, v1
	v_ashrrev_i32_e32 v16, 4, v1
	v_lshlrev_b32_e32 v13, 2, v1
	s_movk_i32 s29, 0xbf
	v_ashrrev_i32_e32 v17, 31, v16
	v_and_b32_e32 v1, 60, v13
	v_cmp_lt_i32_e32 vcc, s29, v162
	s_movk_i32 s29, 0xc0
	v_lshlrev_b64 v[10:11], 19, v[16:17]
	v_ashrrev_i32_e32 v9, 31, v8
	v_cmp_gt_i32_e64 s[40:41], s29, v162
	v_mov_b32_e32 v96, v161
	v_mov_b32_e32 v97, v161
	v_mov_b32_e32 v98, v161
	v_mov_b32_e32 v99, v161
	v_lshlrev_b32_e32 v14, 2, v1
	v_readlane_b32 s60, v241, 6
	v_readlane_b32 s61, v241, 7
	v_readlane_b32 s62, v241, 8
	v_readlane_b32 s63, v241, 9
	v_readlane_b32 s64, v241, 10
	v_readlane_b32 s65, v241, 11
	v_readlane_b32 s66, v241, 12
	v_readlane_b32 s67, v241, 13
	v_readlane_b32 s68, v241, 14
	v_readlane_b32 s69, v241, 15
	v_readlane_b32 s70, v241, 16
	v_readlane_b32 s71, v241, 17
	s_and_saveexec_b64 s[58:59], s[40:41]
	s_cbranch_execz .LBB0_590
	v_lshl_add_u64 v[22:23], s[24:25], 0, v[8:9]
	v_lshl_add_u64 v[20:21], s[18:19], 0, v[10:11]
	v_lshlrev_b64 v[22:23], 13, v[22:23]
	v_lshl_add_u64 v[20:21], v[20:21], 0, v[22:23]
	v_mov_b32_e32 v15, v161
	v_lshl_add_u64 v[20:21], v[20:21], 0, v[14:15]
	s_lshl_b32 s44, s77, 2
	v_lshl_add_u64 v[20:21], v[20:21], 0, s[44:45]
	global_load_dwordx4 v[96:99], v[20:21], off
; #define SD_LOAD(j) do { br0 = *(const u32x4*)(Bp + (size_t)(j) * 16384 + bc0 * 16); br1 = *(const u32x4*)(Bp + (size_t)(j) * 16384 + bc1 * 16); \
;         xr0 = *(const u32x4*)(Xp0 + (j) * 64); xr1 = *(const u32x4*)(Xp1 + (j) * 64); if (tid < 192) vr = *(const f32x4*)(vsrc + (j) * 64); } while (0)
; __device__ __forceinline__ void ssd_item(LAS unsigned char* lds, const Args& a, int b, int hp, int qb) {
;     ...
;     const int j0 = qb * 4, j1 = j0 + 4;
;     __syncthreads();
;     SD_LOAD(j0); SD_STORE(j0 & 1);
;     __syncthreads();
;     f32x16 y[2][2], zero16;
; #pragma unroll
;     for (int i = 0; i < 16; ++i) zero16[i] = 0.f;
; #pragma unroll
;     for (int i = 0; i < 16; ++i) { y[0][0][i] = 0.f; y[0][1][i] = 0.f; y[1][0][i] = 0.f; y[1][1][i] = 0.f; }
;     ...
;         const bf16* Hst = (const bf16*)a.out + HST_OFF;
;         const int Lb = qb * 256;
;         u32x4 hreg[8];
; #pragma unroll
;         for (int tq = 0; tq < 4; ++tq)
; #pragma unroll
;             for (int i = 0; i < 2; ++i) { const int id = tid + 512 * i;
;                 hreg[2 * tq + i] = *(const u32x4*)(Hst + ((((size_t)(b * 8 + h0 + (tq >> 1)) * 2 + (tq & 1)) * 8 + qb) * 64) * 128 + (size_t)id * 8); }
.LBB0_590:
	s_or_b64 exec, exec, s[58:59]
	s_movk_i32 s24, 0x90
	v_lshrrev_b32_e32 v1, 4, v162
	v_mul_lo_u32 v12, v12, s24
	v_lshlrev_b32_e32 v17, 3, v162
	v_mul_lo_u32 v181, v1, s72
	v_and_b32_e32 v182, 0xf0, v4
	v_lshrrev_b32_e32 v1, 4, v104
	v_and_b32_e32 v15, 0x60, v0
	v_and_or_b32 v12, v17, 8, v12
	v_add_u32_e32 v105, v181, v182
	v_mul_lo_u32 v183, v1, s72
	v_mul_lo_u32 v1, v8, 6
	v_add_u32_e32 v184, v12, v15
	v_add_u32_e32 v163, v183, v182
	v_add_lshl_u32 v1, v1, v16, 8
	v_add_u32_e32 v16, 0, v105
	v_add_u32_e32 v12, 0, v184
	s_waitcnt vmcnt(3)
	ds_write_b128 v16, v[80:83]
	v_add_u32_e32 v16, 0, v163
	v_add_u32_e32 v15, 0x4000, v12
	v_add_u32_e32 v12, 0x6800, v12
	v_add_u32_e32 v185, v14, v1
	s_waitcnt vmcnt(2)
	ds_write_b128 v16, v[84:87]
	s_waitcnt vmcnt(1)
	ds_write2_b64 v15, v[88:89], v[90:91] offset0:128 offset1:130
	s_waitcnt vmcnt(0)
	ds_write2_b64 v12, v[92:93], v[94:95] offset1:2
	s_and_saveexec_b64 s[24:25], vcc
	s_xor_b64 s[24:25], exec, s[24:25]
	v_add_u32_e32 v185, v14, v1
	s_or_saveexec_b64 s[24:25], s[24:25]
	v_readlane_b32 s70, v240, 35
	v_readlane_b32 s37, v240, 34
	v_readlane_b32 s71, v240, 36
	s_mov_b64 s[62:63], s[80:81]
	s_mov_b64 s[64:65], s[38:39]
	s_mov_b64 s[66:67], s[96:97]
	s_mov_b64 s[68:69], s[90:91]
	s_xor_b64 exec, exec, s[24:25]
	v_add_u32_e32 v1, 0, v185
	ds_write_b128 v1, v[96:99] offset:35840
	s_or_b64 exec, exec, s[24:25]
	s_add_i32 s26, s75, s26
	s_bfe_u32 s24, s73, 0x30003
	s_and_b32 s25, s27, 3
	s_ashr_i32 s27, s26, 31
	s_lshl_b32 s55, s24, 8
	s_lshl_b32 s29, s24, 16
	s_lshl_b32 s30, s24, 9
	s_lshl_b32 s44, s24, 10
	s_lshl_b32 s24, s78, 2
	s_lshl_b64 s[26:27], s[26:27], 19
	s_lshl_b32 s25, s25, 1
	s_add_i32 s79, s24, 4
	s_or_b32 s26, s26, s29
	s_add_u32 s26, s26, 0xc804000
	s_addc_u32 s27, s27, 0
	v_lshl_add_u64 v[108:109], s[26:27], 0, v[4:5]
	v_lshl_add_u64 v[110:111], s[26:27], 0, v[6:7]
	s_add_i32 s26, s28, s25
	s_ashr_i32 s27, s26, 31
	s_lshl_b64 s[26:27], s[26:27], 18
	s_or_b32 s26, s26, s30
	s_add_u32 s0, s0, s25
	v_lshl_add_u64 v[2:3], s[26:27], 0, v[2:3]
	v_mov_b32_e32 v1, v161
	s_addc_u32 s1, s1, 0
	v_lshl_add_u64 v[112:113], v[2:3], 0, v[0:1]
	v_lshl_add_u64 v[0:1], s[0:1], 0, v[8:9]
	v_lshlrev_b64 v[0:1], 13, v[0:1]
	v_lshl_add_u64 v[0:1], v[10:11], 0, v[0:1]
	v_lshlrev_b32_e32 v2, 2, v13
	v_lshl_add_u64 v[0:1], v[0:1], 0, s[44:45]
	v_and_b32_e32 v2, 0xf0, v2
	v_mov_b32_e32 v3, v161
	v_lshlrev_b32_e32 v188, 2, v18
	v_lshl_add_u64 v[0:1], v[0:1], 0, v[2:3]
	s_mov_b64 s[0:1], 0x7800100
	v_mov_b32_e32 v32, 0
	v_and_b32_e32 v175, 63, v162
	v_or_b32_e32 v186, 31, v164
	v_mul_u32_u24_e32 v187, 0x90, v165
	v_mul_u32_u24_e32 v180, 0x110, v165
	v_mov_b32_e32 v106, v103
	v_mov_b32_e32 v107, v103
	v_mov_b32_e32 v101, v100
	v_mov_b32_e32 v103, v102
	v_or_b32_e32 v189, s55, v188
	v_lshl_add_u64 v[114:115], v[0:1], 0, s[0:1]
	s_mov_b32 s44, 0
	v_mov_b32_e32 v33, v32
	v_mov_b32_e32 v34, v32
	v_mov_b32_e32 v35, v32
	v_mov_b32_e32 v36, v32
	v_mov_b32_e32 v37, v32
	v_mov_b32_e32 v38, v32
	v_mov_b32_e32 v39, v32
	v_mov_b32_e32 v40, v32
	v_mov_b32_e32 v41, v32
	v_mov_b32_e32 v42, v32
	v_mov_b32_e32 v43, v32
	v_mov_b32_e32 v44, v32
	v_mov_b32_e32 v45, v32
	v_mov_b32_e32 v46, v32
	v_mov_b32_e32 v47, v32
	v_mov_b32_e32 v48, v32
	v_mov_b32_e32 v49, v32
	v_mov_b32_e32 v50, v32
	v_mov_b32_e32 v51, v32
	v_mov_b32_e32 v52, v32
	v_mov_b32_e32 v53, v32
	v_mov_b32_e32 v54, v32
	v_mov_b32_e32 v55, v32
	v_mov_b32_e32 v56, v32
	v_mov_b32_e32 v57, v32
	v_mov_b32_e32 v58, v32
	v_mov_b32_e32 v59, v32
	v_mov_b32_e32 v60, v32
	v_mov_b32_e32 v61, v32
	v_mov_b32_e32 v62, v32
	v_mov_b32_e32 v63, v32
	v_mov_b32_e32 v16, v32
	v_mov_b32_e32 v17, v32
	v_mov_b32_e32 v18, v32
	v_mov_b32_e32 v19, v32
	v_mov_b32_e32 v20, v32
	v_mov_b32_e32 v21, v32
	v_mov_b32_e32 v22, v32
	v_mov_b32_e32 v23, v32
	v_mov_b32_e32 v24, v32
	v_mov_b32_e32 v25, v32
	v_mov_b32_e32 v26, v32
	v_mov_b32_e32 v27, v32
	v_mov_b32_e32 v28, v32
	v_mov_b32_e32 v29, v32
	v_mov_b32_e32 v30, v32
	v_mov_b32_e32 v31, v32
	v_mov_b32_e32 v0, v32
	v_mov_b32_e32 v1, v32
	v_mov_b32_e32 v2, v32
	v_mov_b32_e32 v3, v32
	v_mov_b32_e32 v4, v32
	v_mov_b32_e32 v5, v32
	v_mov_b32_e32 v6, v32
	v_mov_b32_e32 v7, v32
	v_mov_b32_e32 v8, v32
	v_mov_b32_e32 v9, v32
	v_mov_b32_e32 v10, v32
	v_mov_b32_e32 v11, v32
	v_mov_b32_e32 v12, v32
	v_mov_b32_e32 v13, v32
	v_mov_b32_e32 v14, v32
	v_mov_b32_e32 v15, v32
	s_waitcnt lgkmcnt(0)
	s_barrier
	s_branch .LBB0_597

; __device__ __forceinline__ unsigned xb_ld(unsigned* p)              { return __hip_atomic_load(p, __ATOMIC_RELAXED, __HIP_MEMORY_SCOPE_AGENT); }
; __device__ __forceinline__ unsigned xb_add(unsigned* p, unsigned v) { return __hip_atomic_fetch_add(p, v, __ATOMIC_RELAXED, __HIP_MEMORY_SCOPE_AGENT); }
; #define XB_SPIN(cond, bar) do { unsigned _sp = 0; while (cond) { __builtin_amdgcn_s_sleep(1); \
;     if ((++_sp & 255u) == 0u) { if (xb_ld(&(bar)[XB_TMO])) break; if (_sp > XB_SPIN_CAP) { atomicAdd(&(bar)[XB_TMO], 1u); break; } } } } while (0)
; __device__ __forceinline__ void xcd_barrier(const XcdBarrier& b) {
;     ...
;         if (old + 1u == (gen + 1u) * nloc) {
;             __builtin_amdgcn_fence(__ATOMIC_RELEASE, "agent");
;             asm volatile("s_waitcnt vmcnt(0)" ::: "memory");
;             const unsigned og = xb_add(&bar[XB_TOP], 1u);
;             const unsigned tg = og / nx;
;             if (og + 1u == (tg + 1u) * nx) xb_add(&bar[XB_TOPGEN], 1u);
;             else XB_SPIN(xb_ld(&bar[XB_TOPGEN]) == tg, bar);
.LBB0_684:
	s_andn2_saveexec_b64 s[18:19], s[18:19]
	s_cbranch_execz .LBB0_704
	v_mov_b32_e32 v3, 0x23030
	ds_read_b32 v3, v3
	s_waitcnt lgkmcnt(0)
	v_readfirstlane_b32 s100, v3
	s_nop 0
	s_cmp_lg_u32 s100, 0
	s_cbranch_scc1 .Lloc_5
	s_mov_b64 s[18:19], exec
	buffer_wbl2 sc1
	s_waitcnt lgkmcnt(0)
	s_waitcnt vmcnt(0)
	v_mbcnt_lo_u32_b32 v1, s18, 0
	v_mbcnt_hi_u32_b32 v1, s19, v1
	v_cmp_eq_u32_e32 vcc, 0, v1
	s_and_saveexec_b64 s[20:21], vcc
	s_cbranch_execz .LBB0_687
	s_bcnt1_i32_b64 s18, s[18:19]
	v_readlane_b32 s4, v240, 16
	v_mov_b32_e32 v2, 0
	v_mov_b32_e32 v3, s18
	v_readlane_b32 s5, v240, 17
	s_nop 4
	global_atomic_add v2, v2, v3, s[4:5] sc0

; __device__ __forceinline__ unsigned xb_add(unsigned* p, unsigned v) { return __hip_atomic_fetch_add(p, v, __ATOMIC_RELAXED, __HIP_MEMORY_SCOPE_AGENT); }
; __device__ __forceinline__ void xcd_barrier(const XcdBarrier& b) {
;     ...
;             xb_add(&bar[XB_XGEN(b.x)], 1u);
;             asm volatile("s_waitcnt vmcnt(0)" ::: "memory");
.Lloc_5:
	s_mov_b64 s[18:19], exec
	v_mbcnt_lo_u32_b32 v0, s18, 0
	v_mbcnt_hi_u32_b32 v0, s19, v0
	v_cmp_eq_u32_e32 vcc, 0, v0
	s_waitcnt vmcnt(0)
	s_and_saveexec_b64 s[20:21], vcc
	s_cbranch_execz .LBB0_703
	s_bcnt1_i32_b64 s18, s[18:19]
	v_readlane_b32 s4, v240, 14
	v_mov_b32_e32 v0, 0
	v_mov_b32_e32 v1, s18
	v_readlane_b32 s5, v240, 15
	s_nop 4
	global_atomic_add v0, v1, s[4:5]
